# pool W=8/16: wave-uniform scalar test skips the per-row halo guards and zero-inits when all halo rows exist
# baseline (speedup 1.0000x reference)
.LBB0_302:
	v_readfirstlane_b32 s95, v130
	s_nop 1
	s_cmp_gt_u32 s95, 6
	s_cselect_b32 s95, 1, 0
	v_cmp_eq_u32_e32 vcc, 2, v129
	s_mov_b64 s[52:53], -1
	s_and_saveexec_b64 s[50:51], vcc
	s_cbranch_execz .LBB0_318
	s_bitcmp1_b32 s95, 0
	s_cbranch_scc1 .Lpf_p8_0
	v_cmp_lt_u32_e32 vcc, 6, v130
	v_mov_b32_e32 v12, 0
	v_mov_b32_e32 v16, 0
	v_mov_b32_e32 v17, 0
	v_mov_b32_e32 v18, 0
	v_mov_b32_e32 v19, 0
	s_and_saveexec_b64 s[52:53], vcc
	s_cbranch_execz .LBB0_305
.Lpf_p8_0:
	v_add_u32_e32 v14, -10, v106
	v_ashrrev_i32_e32 v15, 31, v14
	v_lshlrev_b64 v[14:15], 12, v[14:15]
	v_lshl_add_u64 v[14:15], v[0:1], 0, v[14:15]
	global_load_dwordx4 v[16:19], v[14:15], off
.LBB0_305:
	s_or_b64 exec, exec, s[52:53]
	s_bitcmp1_b32 s95, 0
	s_cbranch_scc1 .Lpf_p8_1
	v_cmp_lt_u32_e32 vcc, 5, v130
	v_mov_b32_e32 v13, 0
	v_mov_b32_e32 v14, 0
	v_mov_b32_e32 v15, 0
	s_and_saveexec_b64 s[52:53], vcc
	s_cbranch_execz .LBB0_307
.Lpf_p8_1:
	v_add_u32_e32 v12, -9, v106
	v_ashrrev_i32_e32 v13, 31, v12
	v_lshlrev_b64 v[12:13], 12, v[12:13]
	v_lshl_add_u64 v[12:13], v[0:1], 0, v[12:13]
	global_load_dwordx4 v[12:15], v[12:13], off
.LBB0_307:
	s_or_b64 exec, exec, s[52:53]
	s_bitcmp1_b32 s95, 0
	s_cbranch_scc1 .Lpf_p8_2
	v_cmp_lt_u32_e32 vcc, 4, v130
	v_mov_b32_e32 v20, 0
	v_mov_b32_e32 v32, 0
	v_mov_b32_e32 v33, 0
	v_mov_b32_e32 v34, 0
	v_mov_b32_e32 v35, 0
	s_and_saveexec_b64 s[52:53], vcc
	s_cbranch_execz .LBB0_309
.Lpf_p8_2:
	v_add_u32_e32 v22, -8, v106
	v_ashrrev_i32_e32 v23, 31, v22
	v_lshlrev_b64 v[22:23], 12, v[22:23]
	v_lshl_add_u64 v[22:23], v[0:1], 0, v[22:23]
	global_load_dwordx4 v[32:35], v[22:23], off

.LBB0_320:
	v_readfirstlane_b32 s94, v130
	s_nop 1
	s_cmp_gt_u32 s94, 14
	s_cselect_b32 s94, 1, 0
	s_bitcmp1_b32 s94, 0
	s_cbranch_scc1 .Lpf_p16_0
	v_cmp_lt_u32_e32 vcc, 14, v130
	v_mov_b32_e32 v12, 0
	v_mov_b32_e32 v48, 0
	v_mov_b32_e32 v49, 0
	v_mov_b32_e32 v50, 0
	v_mov_b32_e32 v51, 0
	s_and_saveexec_b64 s[50:51], vcc
	s_cbranch_execz .LBB0_322
.Lpf_p16_0:
	v_subrev_u32_e32 v14, 18, v106
	v_ashrrev_i32_e32 v15, 31, v14
	v_lshlrev_b64 v[14:15], 12, v[14:15]
	v_lshl_add_u64 v[14:15], v[0:1], 0, v[14:15]
	global_load_dwordx4 v[48:51], v[14:15], off
.LBB0_322:
	s_or_b64 exec, exec, s[50:51]
	s_bitcmp1_b32 s94, 0
	s_cbranch_scc1 .Lpf_p16_1
	v_cmp_lt_u32_e32 vcc, 13, v130
	v_mov_b32_e32 v13, 0
	v_mov_b32_e32 v14, 0
	v_mov_b32_e32 v15, 0
	s_and_saveexec_b64 s[50:51], vcc
	s_cbranch_execz .LBB0_324
.Lpf_p16_1:
	v_subrev_u32_e32 v12, 17, v106
	v_ashrrev_i32_e32 v13, 31, v12
	v_lshlrev_b64 v[12:13], 12, v[12:13]
	v_lshl_add_u64 v[12:13], v[0:1], 0, v[12:13]
	global_load_dwordx4 v[12:15], v[12:13], off
.LBB0_324:
	s_or_b64 exec, exec, s[50:51]
	s_bitcmp1_b32 s94, 0
	s_cbranch_scc1 .Lpf_p16_2
	v_cmp_lt_u32_e32 vcc, 12, v130
	v_mov_b32_e32 v24, 0
	v_mov_b32_e32 v28, 0
	v_mov_b32_e32 v29, 0
	v_mov_b32_e32 v30, 0
	v_mov_b32_e32 v31, 0
	s_and_saveexec_b64 s[50:51], vcc
	s_cbranch_execz .LBB0_326
.Lpf_p16_2:
	v_add_u32_e32 v16, -16, v106
	v_ashrrev_i32_e32 v17, 31, v16
	v_lshlrev_b64 v[16:17], 12, v[16:17]
	v_lshl_add_u64 v[16:17], v[0:1], 0, v[16:17]
	global_load_dwordx4 v[28:31], v[16:17], off
.LBB0_326:
	s_or_b64 exec, exec, s[50:51]
	s_bitcmp1_b32 s94, 0
	s_cbranch_scc1 .Lpf_p16_3
	v_cmp_lt_u32_e32 vcc, 11, v130
	v_mov_b32_e32 v25, 0
	v_mov_b32_e32 v26, 0
	v_mov_b32_e32 v27, 0
	s_and_saveexec_b64 s[50:51], vcc
	s_cbranch_execz .LBB0_328
.Lpf_p16_3:
	v_add_u32_e32 v16, -15, v106
	v_ashrrev_i32_e32 v17, 31, v16
	v_lshlrev_b64 v[16:17], 12, v[16:17]
	v_lshl_add_u64 v[16:17], v[0:1], 0, v[16:17]
	global_load_dwordx4 v[24:27], v[16:17], off
.LBB0_328:
	s_or_b64 exec, exec, s[50:51]
	s_bitcmp1_b32 s94, 0
	s_cbranch_scc1 .Lpf_p16_4
	v_cmp_lt_u32_e32 vcc, 10, v130
	v_mov_b32_e32 v32, 0
	v_mov_b32_e32 v36, 0
	v_mov_b32_e32 v37, 0
	v_mov_b32_e32 v38, 0
	v_mov_b32_e32 v39, 0
	s_and_saveexec_b64 s[50:51], vcc
	s_cbranch_execz .LBB0_330
.Lpf_p16_4:
	v_add_u32_e32 v16, -14, v106
	v_ashrrev_i32_e32 v17, 31, v16
	v_lshlrev_b64 v[16:17], 12, v[16:17]
	v_lshl_add_u64 v[16:17], v[0:1], 0, v[16:17]
	global_load_dwordx4 v[36:39], v[16:17], off
.LBB0_330:
	s_or_b64 exec, exec, s[50:51]
	s_bitcmp1_b32 s94, 0
	s_cbranch_scc1 .Lpf_p16_5
	v_cmp_lt_u32_e32 vcc, 9, v130
	v_mov_b32_e32 v33, 0
	v_mov_b32_e32 v34, 0
	v_mov_b32_e32 v35, 0
	s_and_saveexec_b64 s[50:51], vcc
	s_cbranch_execz .LBB0_332
.Lpf_p16_5:
	v_add_u32_e32 v16, -13, v106
	v_ashrrev_i32_e32 v17, 31, v16
	v_lshlrev_b64 v[16:17], 12, v[16:17]
	v_lshl_add_u64 v[16:17], v[0:1], 0, v[16:17]
	global_load_dwordx4 v[32:35], v[16:17], off
.LBB0_332:
	s_or_b64 exec, exec, s[50:51]
	s_bitcmp1_b32 s94, 0
	s_cbranch_scc1 .Lpf_p16_6
	v_cmp_lt_u32_e32 vcc, 8, v130
	v_mov_b32_e32 v52, 0
	v_mov_b32_e32 v56, 0
	v_mov_b32_e32 v57, 0
	v_mov_b32_e32 v58, 0
	v_mov_b32_e32 v59, 0
	s_and_saveexec_b64 s[50:51], vcc
	s_cbranch_execz .LBB0_334
.Lpf_p16_6:
	v_add_u32_e32 v16, -12, v106
	v_ashrrev_i32_e32 v17, 31, v16
	v_lshlrev_b64 v[16:17], 12, v[16:17]
	v_lshl_add_u64 v[16:17], v[0:1], 0, v[16:17]
	global_load_dwordx4 v[56:59], v[16:17], off
.LBB0_334:
	s_or_b64 exec, exec, s[50:51]
	s_bitcmp1_b32 s94, 0
	s_cbranch_scc1 .Lpf_p16_7
	v_cmp_lt_u32_e32 vcc, 7, v130
	v_mov_b32_e32 v53, 0
	v_mov_b32_e32 v54, 0
	v_mov_b32_e32 v55, 0
	s_and_saveexec_b64 s[50:51], vcc
	s_cbranch_execz .LBB0_336
.Lpf_p16_7:
	v_add_u32_e32 v16, -11, v106
	v_ashrrev_i32_e32 v17, 31, v16
	v_lshlrev_b64 v[16:17], 12, v[16:17]
	v_lshl_add_u64 v[16:17], v[0:1], 0, v[16:17]
	global_load_dwordx4 v[52:55], v[16:17], off
.LBB0_336:
	s_or_b64 exec, exec, s[50:51]
	s_bitcmp1_b32 s94, 0
	s_cbranch_scc1 .Lpf_p16_8
	v_cmp_lt_u32_e32 vcc, 6, v130
	v_mov_b32_e32 v76, 0
	v_mov_b32_e32 v80, 0
	v_mov_b32_e32 v81, 0
	v_mov_b32_e32 v82, 0
	v_mov_b32_e32 v83, 0
	s_and_saveexec_b64 s[50:51], vcc
	s_cbranch_execz .LBB0_338
.Lpf_p16_8:
	v_add_u32_e32 v16, -10, v106
	v_ashrrev_i32_e32 v17, 31, v16
	v_lshlrev_b64 v[16:17], 12, v[16:17]
	v_lshl_add_u64 v[16:17], v[0:1], 0, v[16:17]
	global_load_dwordx4 v[80:83], v[16:17], off
.LBB0_338:
	s_or_b64 exec, exec, s[50:51]
	s_bitcmp1_b32 s94, 0
	s_cbranch_scc1 .Lpf_p16_9
	v_cmp_lt_u32_e32 vcc, 5, v130
	v_mov_b32_e32 v77, 0
	v_mov_b32_e32 v78, 0
	v_mov_b32_e32 v79, 0
	s_and_saveexec_b64 s[50:51], vcc
	s_cbranch_execz .LBB0_340
.Lpf_p16_9:
	v_add_u32_e32 v16, -9, v106
	v_ashrrev_i32_e32 v17, 31, v16
	v_lshlrev_b64 v[16:17], 12, v[16:17]
	v_lshl_add_u64 v[16:17], v[0:1], 0, v[16:17]
	global_load_dwordx4 v[76:79], v[16:17], off
.LBB0_340:
	s_or_b64 exec, exec, s[50:51]
	s_bitcmp1_b32 s94, 0
	s_cbranch_scc1 .Lpf_p16_10
	v_cmp_lt_u32_e32 vcc, 4, v130
	v_mov_b32_e32 v88, 0
	v_mov_b32_e32 v96, 0
	v_mov_b32_e32 v97, 0
	v_mov_b32_e32 v98, 0
	v_mov_b32_e32 v99, 0
	s_and_saveexec_b64 s[50:51], vcc
	s_cbranch_execz .LBB0_342
.Lpf_p16_10:
	v_add_u32_e32 v16, -8, v106
	v_ashrrev_i32_e32 v17, 31, v16
	v_lshlrev_b64 v[16:17], 12, v[16:17]
	v_lshl_add_u64 v[16:17], v[0:1], 0, v[16:17]
	global_load_dwordx4 v[96:99], v[16:17], off
